# GEMM main loop: redundant lgkmcnt(0) between the pre-MFMA barrier and the first MFMA removed (the same wait precedes the barrier)
# speedup vs baseline: 1.0095x; 1.0012x over previous
.LBB0_66:
	v_add_u32_e32 v0, s61, v242
	s_waitcnt lgkmcnt(0)
	ds_read_b128 v[130:133], v0
	ds_read_b128 v[134:137], v0 offset:1024
	ds_read_b128 v[138:141], v0 offset:2048
	ds_read_b128 v[142:145], v0 offset:3072
	v_add_u32_e32 v0, s20, v242
	ds_read_b128 v[146:149], v0
	ds_read_b128 v[150:153], v0 offset:1024
	ds_read_b128 v[154:157], v0 offset:2048
	ds_read_b128 v[158:161], v0 offset:3072
	s_add_i32 s14, s10, 2
	s_add_u32 s15, s0, 0x80
	s_addc_u32 s11, s1, 0
	s_cmp_eq_u32 s27, s10
	s_cselect_b32 s10, s22, s15
	s_cselect_b32 s11, s23, s11
	s_cselect_b32 s53, s25, s13
	s_cselect_b32 s52, s24, s12
	v_lshl_add_u64 v[216:217], s[0:1], 0, v[194:195]
	s_add_i32 m0, s5, 0xc000
	ds_read_b128 v[162:165], v246
	ds_read_b128 v[166:169], v246 offset:1024
	ds_read_b128 v[170:173], v246 offset:2048
	ds_read_b128 v[174:177], v246 offset:3072
	ds_read_b128 v[200:203], v246 offset:4096
	ds_read_b128 v[204:207], v246 offset:5120
	ds_read_b128 v[208:211], v246 offset:6144
	ds_read_b128 v[212:215], v246 offset:7168
	global_load_lds_dwordx4 v[216:217], off
	v_lshl_add_u64 v[216:217], s[0:1], 0, v[196:197]
	s_add_i32 m0, s5, 0xe000
	s_nop 0
	global_load_lds_dwordx4 v[216:217], off
	s_waitcnt vmcnt(8)
	s_waitcnt lgkmcnt(0)
	s_barrier
	v_mfma_f32_16x16x32_bf16 v[30:33], v[130:133], v[162:165], v[30:33]
	v_mfma_f32_16x16x32_bf16 v[26:29], v[138:141], v[162:165], v[26:29]
	v_mfma_f32_16x16x32_bf16 v[18:21], v[130:133], v[170:173], v[18:21]
	v_mfma_f32_16x16x32_bf16 v[10:13], v[138:141], v[170:173], v[10:13]
	v_mfma_f32_16x16x32_bf16 v[126:129], v[130:133], v[200:203], v[126:129]
	v_mfma_f32_16x16x32_bf16 v[122:125], v[138:141], v[200:203], v[122:125]
	v_mfma_f32_16x16x32_bf16 v[110:113], v[130:133], v[208:211], v[110:113]
	v_mfma_f32_16x16x32_bf16 v[106:109], v[138:141], v[208:211], v[106:109]
	v_mfma_f32_16x16x32_bf16 v[30:33], v[134:137], v[166:169], v[30:33]
	v_mfma_f32_16x16x32_bf16 v[26:29], v[142:145], v[166:169], v[26:29]
	v_mfma_f32_16x16x32_bf16 v[18:21], v[134:137], v[174:177], v[18:21]
	v_mfma_f32_16x16x32_bf16 v[10:13], v[142:145], v[174:177], v[10:13]
	v_mfma_f32_16x16x32_bf16 v[126:129], v[134:137], v[204:207], v[126:129]
	v_mfma_f32_16x16x32_bf16 v[122:125], v[142:145], v[204:207], v[122:125]
	v_mfma_f32_16x16x32_bf16 v[110:113], v[134:137], v[212:215], v[110:113]
	v_mfma_f32_16x16x32_bf16 v[106:109], v[142:145], v[212:215], v[106:109]
	v_mfma_f32_16x16x32_bf16 v[22:25], v[146:149], v[162:165], v[22:25]
	v_mfma_f32_16x16x32_bf16 v[14:17], v[154:157], v[162:165], v[14:17]
	v_mfma_f32_16x16x32_bf16 v[6:9], v[146:149], v[170:173], v[6:9]
	v_mfma_f32_16x16x32_bf16 v[2:5], v[154:157], v[170:173], v[2:5]
	v_mfma_f32_16x16x32_bf16 v[118:121], v[146:149], v[200:203], v[118:121]
	v_mfma_f32_16x16x32_bf16 v[114:117], v[154:157], v[200:203], v[114:117]
	v_mfma_f32_16x16x32_bf16 v[102:105], v[146:149], v[208:211], v[102:105]
	v_mfma_f32_16x16x32_bf16 v[98:101], v[154:157], v[208:211], v[98:101]
	v_mfma_f32_16x16x32_bf16 v[22:25], v[150:153], v[166:169], v[22:25]
	v_mfma_f32_16x16x32_bf16 v[14:17], v[158:161], v[166:169], v[14:17]
	v_mfma_f32_16x16x32_bf16 v[6:9], v[150:153], v[174:177], v[6:9]
	v_mfma_f32_16x16x32_bf16 v[2:5], v[158:161], v[174:177], v[2:5]
	v_mfma_f32_16x16x32_bf16 v[118:121], v[150:153], v[204:207], v[118:121]
	v_mfma_f32_16x16x32_bf16 v[114:117], v[158:161], v[204:207], v[114:117]
	v_mfma_f32_16x16x32_bf16 v[102:105], v[150:153], v[212:215], v[102:105]
	v_mfma_f32_16x16x32_bf16 v[98:101], v[158:161], v[212:215], v[98:101]
	s_barrier
	s_mov_b32 m0, s62
	v_lshl_add_u64 v[216:217], s[52:53], 0, v[178:179]
	v_lshl_add_u64 v[218:219], s[52:53], 0, v[180:181]
	s_add_u32 s52, s52, s96
	ds_read_b128 v[162:165], v246 offset:16384
	ds_read_b128 v[166:169], v246 offset:17408
	ds_read_b128 v[170:173], v246 offset:18432
	ds_read_b128 v[174:177], v246 offset:19456
	ds_read_b128 v[200:203], v246 offset:20480
	ds_read_b128 v[204:207], v246 offset:21504
	ds_read_b128 v[208:211], v246 offset:22528
	ds_read_b128 v[212:215], v246 offset:23552
	global_load_lds_dwordx4 v[216:217], off
	s_mov_b32 m0, s63
	s_addc_u32 s53, s53, 0
	global_load_lds_dwordx4 v[218:219], off
	v_lshl_add_u64 v[220:221], s[52:53], 0, v[178:179]
	s_mov_b32 m0, s21
	v_lshl_add_u64 v[222:223], s[52:53], 0, v[180:181]
	global_load_lds_dwordx4 v[220:221], off
	s_mov_b32 m0, s4
	v_lshl_add_u64 v[224:225], s[10:11], 0, v[178:179]
	global_load_lds_dwordx4 v[222:223], off
	s_mov_b32 m0, s5
	v_lshl_add_u64 v[226:227], s[10:11], 0, v[180:181]
	global_load_lds_dwordx4 v[224:225], off
	s_mov_b32 m0, s60
	s_nop 0
	global_load_lds_dwordx4 v[226:227], off
	s_waitcnt vmcnt(8)
	s_waitcnt lgkmcnt(0)
	s_barrier
	v_mfma_f32_16x16x32_bf16 v[94:97], v[130:133], v[162:165], v[94:97]
	v_mfma_f32_16x16x32_bf16 v[90:93], v[138:141], v[162:165], v[90:93]
	v_mfma_f32_16x16x32_bf16 v[78:81], v[130:133], v[170:173], v[78:81]
	v_mfma_f32_16x16x32_bf16 v[74:77], v[138:141], v[170:173], v[74:77]
	v_mfma_f32_16x16x32_bf16 v[62:65], v[130:133], v[200:203], v[62:65]
	v_mfma_f32_16x16x32_bf16 v[58:61], v[138:141], v[200:203], v[58:61]
	v_mfma_f32_16x16x32_bf16 v[46:49], v[130:133], v[208:211], v[46:49]
	v_mfma_f32_16x16x32_bf16 v[42:45], v[138:141], v[208:211], v[42:45]
	v_mfma_f32_16x16x32_bf16 v[94:97], v[134:137], v[166:169], v[94:97]
	v_mfma_f32_16x16x32_bf16 v[90:93], v[142:145], v[166:169], v[90:93]
	v_mfma_f32_16x16x32_bf16 v[78:81], v[134:137], v[174:177], v[78:81]
	v_mfma_f32_16x16x32_bf16 v[74:77], v[142:145], v[174:177], v[74:77]
	v_mfma_f32_16x16x32_bf16 v[62:65], v[134:137], v[204:207], v[62:65]
	v_mfma_f32_16x16x32_bf16 v[58:61], v[142:145], v[204:207], v[58:61]
	v_mfma_f32_16x16x32_bf16 v[46:49], v[134:137], v[212:215], v[46:49]
	v_mfma_f32_16x16x32_bf16 v[42:45], v[142:145], v[212:215], v[42:45]
	v_mfma_f32_16x16x32_bf16 v[86:89], v[146:149], v[162:165], v[86:89]
	v_mfma_f32_16x16x32_bf16 v[82:85], v[154:157], v[162:165], v[82:85]
	v_mfma_f32_16x16x32_bf16 v[70:73], v[146:149], v[170:173], v[70:73]
	v_mfma_f32_16x16x32_bf16 v[66:69], v[154:157], v[170:173], v[66:69]
	v_mfma_f32_16x16x32_bf16 v[54:57], v[146:149], v[200:203], v[54:57]
	v_mfma_f32_16x16x32_bf16 v[50:53], v[154:157], v[200:203], v[50:53]
	v_mfma_f32_16x16x32_bf16 v[38:41], v[146:149], v[208:211], v[38:41]
	v_mfma_f32_16x16x32_bf16 v[34:37], v[154:157], v[208:211], v[34:37]
	v_mfma_f32_16x16x32_bf16 v[86:89], v[150:153], v[166:169], v[86:89]
	v_mfma_f32_16x16x32_bf16 v[82:85], v[158:161], v[166:169], v[82:85]
	v_mfma_f32_16x16x32_bf16 v[70:73], v[150:153], v[174:177], v[70:73]
	v_mfma_f32_16x16x32_bf16 v[66:69], v[158:161], v[174:177], v[66:69]
	v_mfma_f32_16x16x32_bf16 v[54:57], v[150:153], v[204:207], v[54:57]
	v_mfma_f32_16x16x32_bf16 v[50:53], v[158:161], v[204:207], v[50:53]
	v_mfma_f32_16x16x32_bf16 v[38:41], v[150:153], v[212:215], v[38:41]
	v_mfma_f32_16x16x32_bf16 v[34:37], v[158:161], v[212:215], v[34:37]
	s_barrier
	v_add_u32_e32 v0, s6, v242
	ds_read_b128 v[130:133], v0
	ds_read_b128 v[134:137], v0 offset:1024
	ds_read_b128 v[138:141], v0 offset:2048
	ds_read_b128 v[142:145], v0 offset:3072
	v_add_u32_e32 v0, s94, v242
	ds_read_b128 v[146:149], v0
	ds_read_b128 v[150:153], v0 offset:1024
	ds_read_b128 v[154:157], v0 offset:2048
	ds_read_b128 v[158:161], v0 offset:3072
	s_add_u32 s10, s10, s96
	s_addc_u32 s11, s11, 0
	s_mov_b32 m0, s84
	v_lshl_add_u64 v[228:229], s[10:11], 0, v[178:179]
	ds_read_b128 v[162:165], v246 offset:32768
	ds_read_b128 v[166:169], v246 offset:33792
	ds_read_b128 v[170:173], v246 offset:34816
	ds_read_b128 v[174:177], v246 offset:35840
	ds_read_b128 v[200:203], v246 offset:36864
	ds_read_b128 v[204:207], v246 offset:37888
	ds_read_b128 v[208:211], v246 offset:38912
	ds_read_b128 v[212:215], v246 offset:39936
	global_load_lds_dwordx4 v[228:229], off
	v_lshl_add_u64 v[228:229], s[10:11], 0, v[180:181]
	s_mov_b32 m0, s26
	s_nop 0
	global_load_lds_dwordx4 v[228:229], off
	s_waitcnt vmcnt(8)
	s_waitcnt lgkmcnt(0)
	s_barrier
	v_mfma_f32_16x16x32_bf16 v[30:33], v[130:133], v[162:165], v[30:33]
	v_mfma_f32_16x16x32_bf16 v[26:29], v[138:141], v[162:165], v[26:29]
	v_mfma_f32_16x16x32_bf16 v[18:21], v[130:133], v[170:173], v[18:21]
	v_mfma_f32_16x16x32_bf16 v[10:13], v[138:141], v[170:173], v[10:13]
	v_mfma_f32_16x16x32_bf16 v[126:129], v[130:133], v[200:203], v[126:129]
	v_mfma_f32_16x16x32_bf16 v[122:125], v[138:141], v[200:203], v[122:125]
	v_mfma_f32_16x16x32_bf16 v[110:113], v[130:133], v[208:211], v[110:113]
	v_mfma_f32_16x16x32_bf16 v[106:109], v[138:141], v[208:211], v[106:109]
	v_mfma_f32_16x16x32_bf16 v[30:33], v[134:137], v[166:169], v[30:33]
	v_mfma_f32_16x16x32_bf16 v[26:29], v[142:145], v[166:169], v[26:29]
	v_mfma_f32_16x16x32_bf16 v[18:21], v[134:137], v[174:177], v[18:21]
	v_mfma_f32_16x16x32_bf16 v[10:13], v[142:145], v[174:177], v[10:13]
	v_mfma_f32_16x16x32_bf16 v[126:129], v[134:137], v[204:207], v[126:129]
	v_mfma_f32_16x16x32_bf16 v[122:125], v[142:145], v[204:207], v[122:125]
	v_mfma_f32_16x16x32_bf16 v[110:113], v[134:137], v[212:215], v[110:113]
	v_mfma_f32_16x16x32_bf16 v[106:109], v[142:145], v[212:215], v[106:109]
	v_mfma_f32_16x16x32_bf16 v[22:25], v[146:149], v[162:165], v[22:25]
	v_mfma_f32_16x16x32_bf16 v[14:17], v[154:157], v[162:165], v[14:17]
	v_mfma_f32_16x16x32_bf16 v[6:9], v[146:149], v[170:173], v[6:9]
	v_mfma_f32_16x16x32_bf16 v[2:5], v[154:157], v[170:173], v[2:5]
	v_mfma_f32_16x16x32_bf16 v[118:121], v[146:149], v[200:203], v[118:121]
	v_mfma_f32_16x16x32_bf16 v[114:117], v[154:157], v[200:203], v[114:117]
	v_mfma_f32_16x16x32_bf16 v[102:105], v[146:149], v[208:211], v[102:105]
	v_mfma_f32_16x16x32_bf16 v[98:101], v[154:157], v[208:211], v[98:101]
	v_mfma_f32_16x16x32_bf16 v[22:25], v[150:153], v[166:169], v[22:25]
	v_mfma_f32_16x16x32_bf16 v[14:17], v[158:161], v[166:169], v[14:17]
	v_mfma_f32_16x16x32_bf16 v[6:9], v[150:153], v[174:177], v[6:9]
	v_mfma_f32_16x16x32_bf16 v[2:5], v[158:161], v[174:177], v[2:5]
	v_mfma_f32_16x16x32_bf16 v[118:121], v[150:153], v[204:207], v[118:121]
	v_mfma_f32_16x16x32_bf16 v[114:117], v[158:161], v[204:207], v[114:117]
	v_mfma_f32_16x16x32_bf16 v[102:105], v[150:153], v[212:215], v[102:105]
	v_mfma_f32_16x16x32_bf16 v[98:101], v[158:161], v[212:215], v[98:101]
	s_barrier
	s_mov_b32 m0, s7
	v_lshl_add_u64 v[216:217], v[216:217], 0, s[58:59]
	ds_read_b128 v[162:165], v246 offset:49152
	ds_read_b128 v[166:169], v246 offset:50176
	ds_read_b128 v[170:173], v246 offset:51200
	ds_read_b128 v[174:177], v246 offset:52224
	ds_read_b128 v[200:203], v246 offset:53248
	ds_read_b128 v[204:207], v246 offset:54272
	ds_read_b128 v[208:211], v246 offset:55296
	ds_read_b128 v[212:215], v246 offset:56320
	global_load_lds_dwordx4 v[216:217], off
	v_lshl_add_u64 v[216:217], v[218:219], 0, s[58:59]
	s_mov_b32 m0, s86
	s_nop 0
	global_load_lds_dwordx4 v[216:217], off
	v_lshl_add_u64 v[216:217], v[220:221], 0, s[58:59]
	s_mov_b32 m0, s95
	s_nop 0
	global_load_lds_dwordx4 v[216:217], off
	v_lshl_add_u64 v[216:217], v[222:223], 0, s[58:59]
	s_mov_b32 m0, s74
	s_nop 0
	global_load_lds_dwordx4 v[216:217], off
	v_lshl_add_u64 v[216:217], v[224:225], 0, s[58:59]
	s_mov_b32 m0, s87
	s_nop 0
	global_load_lds_dwordx4 v[216:217], off
	v_lshl_add_u64 v[216:217], v[226:227], 0, s[58:59]
	s_mov_b32 m0, s75
	s_nop 0
	global_load_lds_dwordx4 v[216:217], off
	s_waitcnt vmcnt(8)
	s_waitcnt lgkmcnt(0)
	s_barrier
	v_mfma_f32_16x16x32_bf16 v[94:97], v[130:133], v[162:165], v[94:97]
	v_mfma_f32_16x16x32_bf16 v[90:93], v[138:141], v[162:165], v[90:93]
	v_mfma_f32_16x16x32_bf16 v[78:81], v[130:133], v[170:173], v[78:81]
	v_mfma_f32_16x16x32_bf16 v[74:77], v[138:141], v[170:173], v[74:77]
	v_mfma_f32_16x16x32_bf16 v[62:65], v[130:133], v[200:203], v[62:65]
	v_mfma_f32_16x16x32_bf16 v[58:61], v[138:141], v[200:203], v[58:61]
	v_mfma_f32_16x16x32_bf16 v[46:49], v[130:133], v[208:211], v[46:49]
	v_mfma_f32_16x16x32_bf16 v[42:45], v[138:141], v[208:211], v[42:45]
	v_mfma_f32_16x16x32_bf16 v[94:97], v[134:137], v[166:169], v[94:97]
	v_mfma_f32_16x16x32_bf16 v[90:93], v[142:145], v[166:169], v[90:93]
	v_mfma_f32_16x16x32_bf16 v[78:81], v[134:137], v[174:177], v[78:81]
	v_mfma_f32_16x16x32_bf16 v[74:77], v[142:145], v[174:177], v[74:77]
	v_mfma_f32_16x16x32_bf16 v[62:65], v[134:137], v[204:207], v[62:65]
	v_mfma_f32_16x16x32_bf16 v[58:61], v[142:145], v[204:207], v[58:61]
	v_mfma_f32_16x16x32_bf16 v[46:49], v[134:137], v[212:215], v[46:49]
	v_mfma_f32_16x16x32_bf16 v[42:45], v[142:145], v[212:215], v[42:45]
	v_mfma_f32_16x16x32_bf16 v[86:89], v[146:149], v[162:165], v[86:89]
	v_mfma_f32_16x16x32_bf16 v[82:85], v[154:157], v[162:165], v[82:85]
	v_mfma_f32_16x16x32_bf16 v[70:73], v[146:149], v[170:173], v[70:73]
	v_mfma_f32_16x16x32_bf16 v[66:69], v[154:157], v[170:173], v[66:69]
	v_mfma_f32_16x16x32_bf16 v[54:57], v[146:149], v[200:203], v[54:57]
	v_mfma_f32_16x16x32_bf16 v[50:53], v[154:157], v[200:203], v[50:53]
	v_mfma_f32_16x16x32_bf16 v[38:41], v[146:149], v[208:211], v[38:41]
	v_mfma_f32_16x16x32_bf16 v[34:37], v[154:157], v[208:211], v[34:37]
	v_mfma_f32_16x16x32_bf16 v[86:89], v[150:153], v[166:169], v[86:89]
	v_mfma_f32_16x16x32_bf16 v[82:85], v[158:161], v[166:169], v[82:85]
	v_mfma_f32_16x16x32_bf16 v[70:73], v[150:153], v[174:177], v[70:73]
	v_mfma_f32_16x16x32_bf16 v[66:69], v[158:161], v[174:177], v[66:69]
	v_mfma_f32_16x16x32_bf16 v[54:57], v[150:153], v[204:207], v[54:57]
	v_mfma_f32_16x16x32_bf16 v[50:53], v[158:161], v[204:207], v[50:53]
	v_mfma_f32_16x16x32_bf16 v[38:41], v[150:153], v[212:215], v[38:41]
	v_mfma_f32_16x16x32_bf16 v[34:37], v[158:161], v[212:215], v[34:37]
	s_barrier
	s_add_u32 s0, s0, 0x100
	s_addc_u32 s1, s1, 0
	s_add_u32 s12, s12, 0x100
	s_addc_u32 s13, s13, 0
	s_cmp_ge_u32 s14, s33
	s_mov_b32 s10, s14
	s_cbranch_scc0 .LBB0_66
	v_readlane_b32 s0, v254, 13
	v_readlane_b32 s1, v254, 14
	s_and_b64 vcc, exec, s[0:1]
	s_cbranch_vccz .LBB0_69
	s_barrier
